# attention loop: packed f32 ops beside the MFMAs replaced by scalar pairs (score mul/fma/distance update, accumulator rescale)
# speedup vs baseline: 1.0051x; 1.0005x over previous
.LBB0_413:
	v_bitop3_b32 v64, s45, v142, v189 bitop3:0x36
	v_bitop3_b32 v72, s45, v143, v189 bitop3:0x36
	v_bitop3_b32 v80, s44, v142, v189 bitop3:0x36
	v_bitop3_b32 v88, s44, v143, v189 bitop3:0x36
	v_mad_i32_i24 v68, v64, s18, v122
	v_mad_i32_i24 v76, v72, s18, v122
	v_mad_i32_i24 v84, v80, s18, v122
	v_mad_i32_i24 v92, v88, s18, v122
	ds_read_b128 v[64:67], v68 offset:18496
	ds_read_b128 v[68:71], v68 offset:18432
	ds_read_b128 v[72:75], v76 offset:18496
	ds_read_b128 v[76:79], v76 offset:18432
	ds_read_b128 v[80:83], v84 offset:18496
	ds_read_b128 v[84:87], v84 offset:18432
	ds_read_b128 v[88:91], v92 offset:18496
	ds_read_b128 v[92:95], v92 offset:18432
	s_waitcnt lgkmcnt(0)
	v_mfma_f32_16x16x32_bf16 v[92:95], v[92:95], v[56:59], 0
	v_cmp_gt_u32_e64 s[60:61], s97, v160
	v_cmp_gt_u32_e64 s[62:63], s97, v161
	v_cmp_gt_u32_e64 s[64:65], s97, v162
	v_cmp_gt_u32_e64 s[72:73], s97, v163
	v_mfma_f32_16x16x32_bf16 v[108:111], v[88:91], v[60:63], v[92:95]
	s_cmp_lt_i32 s51, s42
	s_cselect_b32 s101, s97, 0
	s_cselect_b64 s[2:3], -1, 0
	s_cmp_lg_u64 s[2:3], 0
	v_mfma_f32_16x16x32_bf16 v[84:87], v[84:87], v[56:59], 0
	s_addc_u32 s44, s51, 0
	v_mov_b32_e32 v153, v97
	v_mov_b32_e32 v154, v96
	v_cmp_gt_u32_e64 s[74:75], s97, v164
	v_cmp_gt_u32_e64 s[92:93], s97, v165
	v_cmp_gt_u32_e64 s[94:95], s97, v166
	v_cmp_gt_u32_e64 s[98:99], s97, v167
	s_lshl_b32 s52, s44, 5
	s_lshr_b32 s45, s51, 2
	v_mul_f32_e32 v108, v126, v108
	v_mul_f32_e32 v109, v126, v109
	v_mul_f32_e32 v110, v126, v110
	v_mul_f32_e32 v111, v126, v111
	v_fma_f32 v108, -v129, v160, v108
	v_fma_f32 v109, -v129, v161, v109
	v_fma_f32 v110, -v129, v162, v110
	v_fma_f32 v111, -v129, v163, v111
	v_mfma_f32_16x16x32_bf16 v[104:107], v[80:83], v[60:63], v[84:87]
	v_cndmask_b32_e64 v155, v144, v108, s[60:61]
	v_cndmask_b32_e64 v156, v144, v109, s[62:63]
	v_cndmask_b32_e64 v110, v144, v110, s[64:65]
	v_cndmask_b32_e64 v111, v144, v111, s[72:73]
	v_mfma_f32_16x16x32_bf16 v[76:79], v[76:79], v[56:59], 0
	v_max3_f32 v157, v155, s30, v156
	v_max3_f32 v157, v157, v110, v111
	v_add_f32_e32 v160, v176, v160
	v_add_f32_e32 v161, v176, v161
	v_add_f32_e32 v162, v176, v162
	v_add_f32_e32 v163, v176, v163
	v_cmp_gt_u32_e64 s[60:61], s101, v168
	v_cmp_gt_u32_e64 s[62:63], s101, v169
	v_cmp_gt_u32_e64 s[64:65], s101, v170
	v_cmp_gt_u32_e64 s[72:73], s101, v171
	s_xor_b32 s45, s45, s17
	s_lshl_b32 s45, s45, 7
	v_mul_f32_e32 v104, v126, v104
	v_mul_f32_e32 v105, v126, v105
	v_mul_f32_e32 v106, v126, v106
	v_mul_f32_e32 v107, v126, v107
	v_fma_f32 v104, -v129, v164, v104
	v_fma_f32 v105, -v129, v165, v105
	v_fma_f32 v106, -v129, v166, v106
	v_fma_f32 v107, -v129, v167, v107
	v_mfma_f32_16x16x32_bf16 v[100:103], v[72:75], v[60:63], v[76:79]
	v_cndmask_b32_e64 v108, v144, v104, s[74:75]
	v_cndmask_b32_e64 v109, v144, v105, s[92:93]
	v_cndmask_b32_e64 v106, v144, v106, s[94:95]
	v_cndmask_b32_e64 v107, v144, v107, s[98:99]
	v_mfma_f32_16x16x32_bf16 v[68:71], v[68:71], v[56:59], 0
	v_max3_f32 v157, v157, v108, v109
	v_max3_f32 v157, v157, v106, v107
	v_add_f32_e32 v164, v176, v164
	v_add_f32_e32 v165, v176, v165
	v_add_f32_e32 v166, v176, v166
	v_add_f32_e32 v167, v176, v167
	v_cmp_gt_u32_e64 s[74:75], s101, v172
	v_cmp_gt_u32_e64 s[92:93], s101, v173
	v_cmp_gt_u32_e64 s[94:95], s101, v174
	v_cmp_gt_u32_e64 s[98:99], s101, v175
	s_and_b32 s45, s45, 0x80
	s_and_b32 s50, s43, 0x60
	v_mul_f32_e32 v100, v126, v100
	v_mul_f32_e32 v101, v126, v101
	v_mul_f32_e32 v102, v126, v102
	v_mul_f32_e32 v103, v126, v103
	v_fma_f32 v100, -v129, v168, v100
	v_fma_f32 v101, -v129, v169, v101
	v_fma_f32 v102, -v129, v170, v102
	v_fma_f32 v103, -v129, v171, v103
	v_mfma_f32_16x16x32_bf16 v[96:99], v[64:67], v[60:63], v[68:71]
	v_cndmask_b32_e64 v104, v144, v100, s[60:61]
	v_cndmask_b32_e64 v105, v144, v101, s[62:63]
	v_cndmask_b32_e64 v102, v144, v102, s[64:65]
	v_cndmask_b32_e64 v103, v144, v103, s[72:73]
	v_max3_f32 v157, v157, v104, v105
	v_max3_f32 v157, v157, v102, v103
	v_add_f32_e32 v168, v176, v168
	v_add_f32_e32 v169, v176, v169
	v_add_f32_e32 v170, v176, v170
	v_add_f32_e32 v171, v176, v171
	s_or_b32 s45, s45, s50
	s_nop 1
	v_mul_f32_e32 v96, v126, v96
	v_mul_f32_e32 v97, v126, v97
	v_mul_f32_e32 v98, v126, v98
	v_mul_f32_e32 v99, v126, v99
	v_fma_f32 v96, -v129, v172, v96
	v_fma_f32 v97, -v129, v173, v97
	v_fma_f32 v98, -v129, v174, v98
	v_fma_f32 v99, -v129, v175, v99
	v_cndmask_b32_e64 v100, v144, v96, s[74:75]
	v_cndmask_b32_e64 v101, v144, v97, s[92:93]
	v_cndmask_b32_e64 v98, v144, v98, s[94:95]
	v_cndmask_b32_e64 v97, v144, v99, s[98:99]
	v_max3_f32 v157, v157, v100, v101
	v_max3_f32 v96, v157, v98, v97
	v_add_f32_e32 v172, v176, v172
	v_add_f32_e32 v173, v176, v173
	v_add_f32_e32 v174, v176, v174
	v_add_f32_e32 v175, v176, v175
	ds_bpermute_b32 v99, v150, v96
	s_lshr_b32 s50, s44, 2
	s_xor_b32 s50, s50, s17
	v_bitop3_b32 v64, s45, v123, v143 bitop3:0xde
	s_lshl_b32 s50, s50, 7
	s_waitcnt lgkmcnt(0)
	v_max_f32_e32 v99, v99, v99
	v_max_f32_e32 v96, v96, v99
	ds_bpermute_b32 v99, v151, v96
	v_mad_u32_u24 v76, v64, s18, 0
	v_bitop3_b32 v64, s45, v130, v143 bitop3:0xde
	s_and_b32 s50, s50, 0x80
	s_and_b32 s44, s52, 0x60
	s_waitcnt lgkmcnt(0)
	v_max3_f32 v96, v154, v96, v99
	v_sub_f32_e32 v127, v155, v96
	v_exp_f32_e32 v127, v127
	v_sub_f32_e32 v128, v156, v96
	v_exp_f32_e32 v128, v128
	v_sub_f32_e32 v110, v110, v96
	v_mad_u32_u24 v78, v64, s18, 0
	v_exp_f32_e32 v110, v110
	v_sub_f32_e32 v111, v111, v96
	s_or_b32 s44, s50, s44
	v_add_u32_e32 v72, v76, v125
	v_add_u32_e32 v74, v78, v125
	v_add_u32_e32 v76, v76, v131
	v_add_u32_e32 v78, v78, v131
	v_exp_f32_e32 v111, v111
	v_sub_f32_e32 v108, v108, v96
	v_sub_f32_e32 v97, v97, v96
	ds_read_b64_tr_b16 v[70:71], v74 offset:55296
	ds_read_b64_tr_b16 v[66:67], v74 offset:55328
	ds_read_b64_tr_b16 v[68:69], v72 offset:55296
	ds_read_b64_tr_b16 v[64:65], v72 offset:55328
	ds_read_b64_tr_b16 v[72:73], v72 offset:55360
	ds_read_b64_tr_b16 v[74:75], v74 offset:55360
	ds_read_b64_tr_b16 v[76:77], v76 offset:55296
	ds_read_b64_tr_b16 v[78:79], v78 offset:55296
	v_bitop3_b32 v80, s44, v123, v143 bitop3:0xde
	v_exp_f32_e32 v108, v108
	v_sub_f32_e32 v109, v109, v96
	v_exp_f32_e32 v158, v97
	v_add_f32_e32 v97, 0, v127
	v_mad_u32_u24 v92, v80, s18, 0
	v_bitop3_b32 v80, s44, v130, v143 bitop3:0xde
	v_exp_f32_e32 v109, v109
	v_sub_f32_e32 v106, v106, v96
	v_add_f32_e32 v97, v128, v97
	v_mad_u32_u24 v94, v80, s18, 0
	v_exp_f32_e32 v106, v106
	v_sub_f32_e32 v107, v107, v96
	v_sub_f32_e32 v102, v102, v96
	v_add_f32_e32 v97, v110, v97
	v_add_u32_e32 v88, v92, v125
	v_add_u32_e32 v90, v94, v125
	v_add_u32_e32 v92, v92, v131
	v_add_u32_e32 v94, v94, v131
	v_sub_f32_e32 v99, v154, v96
	v_exp_f32_e32 v107, v107
	v_sub_f32_e32 v104, v104, v96
	v_exp_f32_e32 v154, v102
	v_sub_f32_e32 v102, v103, v96
	v_add_f32_e32 v97, v111, v97
	ds_read_b64_tr_b16 v[86:87], v90 offset:55296
	ds_read_b64_tr_b16 v[82:83], v90 offset:55328
	ds_read_b64_tr_b16 v[84:85], v88 offset:55296
	ds_read_b64_tr_b16 v[80:81], v88 offset:55328
	ds_read_b64_tr_b16 v[88:89], v88 offset:55360
	ds_read_b64_tr_b16 v[90:91], v90 offset:55360
	ds_read_b64_tr_b16 v[92:93], v92 offset:55296
	ds_read_b64_tr_b16 v[94:95], v94 offset:55296
	v_exp_f32_e32 v104, v104
	v_sub_f32_e32 v105, v105, v96
	v_exp_f32_e32 v103, v102
	v_exp_f32_e32 v102, v99
	v_add_f32_e32 v97, v108, v97
	s_add_i32 s50, s51, 2
	v_exp_f32_e32 v105, v105
	v_add_f32_e32 v97, v109, v97
	s_min_i32 s44, s50, s42
	v_sub_f32_e32 v100, v100, v96
	v_add_f32_e32 v97, v106, v97
	s_add_i32 s45, s51, 3
	s_lshr_b32 s51, s44, 2
	v_exp_f32_e32 v155, v100
	v_sub_f32_e32 v100, v101, v96
	v_sub_f32_e32 v98, v98, v96
	v_add_f32_e32 v97, v107, v97
	s_xor_b32 s51, s51, s17
	v_exp_f32_e32 v156, v100
	v_exp_f32_e32 v157, v98
	v_mul_f32_e32 v54, v102, v54
	v_mul_f32_e32 v55, v102, v55
	v_mul_f32_e32 v52, v102, v52
	v_mul_f32_e32 v53, v102, v53
	v_mul_f32_e32 v50, v102, v50
	v_mul_f32_e32 v51, v102, v51
	v_mul_f32_e32 v48, v102, v48
	v_mul_f32_e32 v49, v102, v49
	v_mul_f32_e32 v46, v102, v46
	v_mul_f32_e32 v47, v102, v47
	v_mul_f32_e32 v44, v102, v44
	v_mul_f32_e32 v45, v102, v45
	v_mul_f32_e32 v42, v102, v42
	v_mul_f32_e32 v43, v102, v43
	v_mul_f32_e32 v40, v102, v40
	v_mul_f32_e32 v41, v102, v41
	v_add_f32_e32 v97, v104, v97
	v_cvt_pk_bf16_f32 v98, v127, v128
	v_cvt_pk_bf16_f32 v99, v110, v111
	v_cvt_pk_bf16_f32 v100, v108, v109
	v_cvt_pk_bf16_f32 v101, v106, v107
	s_lshl_b32 s51, s51, 7
	s_lshl_b32 s44, s44, 5
	v_add_f32_e32 v97, v105, v97
	s_waitcnt lgkmcnt(13)
	v_mfma_f32_16x16x32_bf16 v[52:55], v[68:71], v[98:101], v[52:55]
	s_min_i32 s45, s45, s42
	s_and_b32 s51, s51, 0x80
	s_and_b32 s44, s44, 0x60
	s_waitcnt lgkmcnt(12)
	v_mfma_f32_16x16x32_bf16 v[48:51], v[64:67], v[98:101], v[48:51]
	v_add_f32_e32 v97, v154, v97
	s_or_b32 s44, s51, s44
	s_lshr_b32 s51, s45, 2
	s_waitcnt lgkmcnt(10)
	v_mfma_f32_16x16x32_bf16 v[44:47], v[72:75], v[98:101], v[44:47]
	v_add_f32_e32 v97, v103, v97
	s_xor_b32 s51, s51, s17
	v_add_f32_e32 v97, v155, v97
	s_waitcnt lgkmcnt(8)
	v_mfma_f32_16x16x32_bf16 v[40:43], v[76:79], v[98:101], v[40:43]
	v_cvt_pk_bf16_f32 v64, v104, v105
	v_cvt_pk_bf16_f32 v65, v154, v103
	v_cvt_pk_bf16_f32 v66, v155, v156
	v_cvt_pk_bf16_f32 v67, v157, v158
	s_lshl_b32 s51, s51, 7
	s_lshl_b32 s45, s45, 5
	v_add_f32_e32 v97, v156, v97
	s_waitcnt lgkmcnt(5)
	v_mfma_f32_16x16x32_bf16 v[52:55], v[84:87], v[64:67], v[52:55]
	s_and_b32 s51, s51, 0x80
	s_and_b32 s45, s45, 0x60
	v_add_f32_e32 v97, v157, v97
	s_waitcnt lgkmcnt(4)
	v_mfma_f32_16x16x32_bf16 v[48:51], v[80:83], v[64:67], v[48:51]
	s_or_b32 s45, s51, s45
	v_add_f32_e32 v97, v158, v97
	s_add_i32 s43, s43, 64
	s_waitcnt lgkmcnt(2)
	v_mfma_f32_16x16x32_bf16 v[44:47], v[88:91], v[64:67], v[44:47]
	v_fmac_f32_e32 v97, v153, v102
	v_subrev_u32_e32 v152, 64, v152
	s_cmp_gt_i32 s50, s42
	s_waitcnt lgkmcnt(0)
	v_mfma_f32_16x16x32_bf16 v[40:43], v[92:95], v[64:67], v[40:43]
	s_mov_b32 s51, s50
	s_cbranch_scc0 .LBB0_413
	s_mov_b64 s[2:3], 0
